# NSA top-16 selection: per-round remove-the-max pass replaced by a subtract-and-max formulation (keys left in place)
# baseline (speedup 1.0000x reference)
; DEV void attn_nsa_phase(LAS unsigned char* lds, unsigned char* ws, int tid0, int G, int c) {
;     ...
; #pragma unroll
;             for (int k = 0; k < 16; ++k) { const int s = l8 + 8 * k; const float v = impA[q2 * 128 + s] + impB[q2 * 132 + s];
;                 const bool valid = s <= cur; const bool forced = (s == 0) || (s == cur) || (s == cur - 1);
;                 const unsigned bits = __builtin_bit_cast(unsigned, fmaxf(v, 0.f));
;                 key[k] = valid ? ((forced ? 0xFFFFFF00u : (bits & 0xFFFFFF00u)) | (unsigned)(255 - s)) : 0u; }
.LBB0_2747:
	s_waitcnt lgkmcnt(0)
	s_add_i32 s0, 0, 0x1b800
	v_ashrrev_i32_e32 v0, 3, v83
	v_add_u32_e32 v0, s43, v0
	s_waitcnt vmcnt(0)
	v_and_b32_e32 v21, 7, v83
	v_lshlrev_b32_e32 v2, 9, v0
	v_lshlrev_b32_e32 v4, 2, v21
	v_mul_lo_u32 v3, v0, s44
	v_add3_u32 v19, s91, v2, v4
	v_add3_u32 v20, s0, v3, v4
	ds_read2_b32 v[2:3], v19 offset1:8
	ds_read2_b32 v[4:5], v20 offset1:8
	s_add_i32 s5, s82, -1
	v_cmp_eq_u32_e32 vcc, 0, v21
	v_cmp_eq_u32_e64 s[0:1], s82, v21
	s_or_b64 s[6:7], vcc, s[0:1]
	s_waitcnt lgkmcnt(0)
	v_add_f32_e32 v2, v2, v4
	v_cmp_eq_u32_e64 s[0:1], s5, v21
	v_max_f32_e32 v2, 0, v2
	v_and_b32_e32 v2, 0xffffff00, v2
	s_or_b64 s[0:1], s[6:7], s[0:1]
	v_cndmask_b32_e64 v2, v2, v219, s[0:1]
	v_bitop3_b32 v2, v2, s67, v21 bitop3:0x36
	v_cmp_ge_i32_e64 s[0:1], s82, v21
	v_or_b32_e32 v7, 8, v21
	v_cmp_eq_u32_e64 s[6:7], s5, v7
	v_cndmask_b32_e64 v6, 0, v2, s[0:1]
	v_add_f32_e32 v2, v3, v5
	v_cmp_eq_u32_e64 s[0:1], s82, v7
	v_max_f32_e32 v2, 0, v2
	v_and_b32_e32 v2, 0xffffff00, v2
	s_or_b64 s[0:1], s[0:1], s[6:7]
	v_cndmask_b32_e64 v2, v2, v219, s[0:1]
	s_movk_i32 s0, 0xf7
	v_bitop3_b32 v8, v2, s0, v21 bitop3:0x36
	ds_read2_b32 v[2:3], v19 offset0:16 offset1:24
	ds_read2_b32 v[4:5], v20 offset0:16 offset1:24
	v_cmp_ge_i32_e64 s[0:1], s82, v7
	v_or_b32_e32 v9, 24, v21
	v_or_b32_e32 v11, 40, v21
	v_cndmask_b32_e64 v7, 0, v8, s[0:1]
	v_or_b32_e32 v8, 16, v21
	s_waitcnt lgkmcnt(0)
	v_add_f32_e32 v2, v2, v4
	v_cmp_eq_u32_e64 s[0:1], s82, v8
	v_cmp_eq_u32_e64 s[6:7], s5, v8
	v_max_f32_e32 v2, 0, v2
	v_and_b32_e32 v2, 0xffffff00, v2
	s_or_b64 s[0:1], s[0:1], s[6:7]
	v_cndmask_b32_e64 v2, v2, v219, s[0:1]
	s_movk_i32 s0, 0xef
	v_bitop3_b32 v2, v2, s0, v21 bitop3:0x36
	v_cmp_ge_i32_e64 s[0:1], s82, v8
	v_cmp_eq_u32_e64 s[6:7], s5, v9
	v_or_b32_e32 v13, 56, v21
	v_cndmask_b32_e64 v8, 0, v2, s[0:1]
	v_add_f32_e32 v2, v3, v5
	v_cmp_eq_u32_e64 s[0:1], s82, v9
	v_max_f32_e32 v2, 0, v2
	v_and_b32_e32 v2, 0xffffff00, v2
	s_or_b64 s[0:1], s[0:1], s[6:7]
	v_cndmask_b32_e64 v10, v2, v219, s[0:1]
	ds_read2_b32 v[2:3], v19 offset0:32 offset1:40
	ds_read2_b32 v[4:5], v20 offset0:32 offset1:40
	s_movk_i32 s0, 0xe7
	v_bitop3_b32 v10, v10, s0, v21 bitop3:0x36
	v_cmp_ge_i32_e64 s[0:1], s82, v9
	v_or_b32_e32 v15, 0x48, v21
	s_waitcnt lgkmcnt(0)
	v_add_f32_e32 v2, v2, v4
	v_cndmask_b32_e64 v9, 0, v10, s[0:1]
	v_or_b32_e32 v10, 32, v21
	v_cmp_eq_u32_e64 s[0:1], s82, v10
	v_cmp_eq_u32_e64 s[6:7], s5, v10
	v_max_f32_e32 v2, 0, v2
	v_and_b32_e32 v2, 0xffffff00, v2
	s_or_b64 s[0:1], s[0:1], s[6:7]
	v_cndmask_b32_e64 v2, v2, v219, s[0:1]
	s_movk_i32 s0, 0xdf
	v_bitop3_b32 v2, v2, s0, v21 bitop3:0x36
	v_cmp_ge_i32_e64 s[0:1], s82, v10
	v_cmp_eq_u32_e64 s[6:7], s5, v11
	v_or_b32_e32 v17, 0x58, v21
	v_cndmask_b32_e64 v10, 0, v2, s[0:1]
	v_add_f32_e32 v2, v3, v5
	v_cmp_eq_u32_e64 s[0:1], s82, v11
	v_max_f32_e32 v2, 0, v2
	v_and_b32_e32 v2, 0xffffff00, v2
	s_or_b64 s[0:1], s[0:1], s[6:7]
	v_cndmask_b32_e64 v12, v2, v219, s[0:1]
	ds_read2_b32 v[2:3], v19 offset0:48 offset1:56
	ds_read2_b32 v[4:5], v20 offset0:48 offset1:56
	v_bitop3_b32 v12, v12, s68, v21 bitop3:0x36
	v_cmp_ge_i32_e64 s[0:1], s82, v11
	v_or_b32_e32 v22, 0x68, v21
	s_mov_b32 s4, 16
	v_cndmask_b32_e64 v11, 0, v12, s[0:1]
	v_or_b32_e32 v12, 48, v21
	s_waitcnt lgkmcnt(0)
	v_add_f32_e32 v2, v2, v4
	v_cmp_eq_u32_e64 s[0:1], s82, v12
	v_cmp_eq_u32_e64 s[6:7], s5, v12
	v_max_f32_e32 v2, 0, v2
	v_and_b32_e32 v2, 0xffffff00, v2
	s_or_b64 s[0:1], s[0:1], s[6:7]
	v_cndmask_b32_e64 v2, v2, v219, s[0:1]
	v_bitop3_b32 v2, v2, s69, v21 bitop3:0x36
	v_cmp_ge_i32_e64 s[0:1], s82, v12
	v_cmp_eq_u32_e64 s[6:7], s5, v13
	v_xor_b32_e32 v24, 16, v82
	v_cndmask_b32_e64 v12, 0, v2, s[0:1]
	v_add_f32_e32 v2, v3, v5
	v_cmp_eq_u32_e64 s[0:1], s82, v13
	v_max_f32_e32 v2, 0, v2
	v_and_b32_e32 v2, 0xffffff00, v2
	s_or_b64 s[0:1], s[0:1], s[6:7]
	v_cndmask_b32_e64 v14, v2, v219, s[0:1]
	ds_read2_b32 v[2:3], v19 offset0:64 offset1:72
	ds_read2_b32 v[4:5], v20 offset0:64 offset1:72
	v_bitop3_b32 v14, v14, s70, v21 bitop3:0x36
	v_cmp_ge_i32_e64 s[0:1], s82, v13
	s_waitcnt lgkmcnt(0)
; DEV void attn_nsa_phase(LAS unsigned char* lds, unsigned char* ws, int tid0, int G, int c) {
;     ...
; #pragma unroll
;             for (int k = 0; k < 16; ++k) { const int s = l8 + 8 * k; const float v = impA[q2 * 128 + s] + impB[q2 * 132 + s];
;                 const bool valid = s <= cur; const bool forced = (s == 0) || (s == cur) || (s == cur - 1);
;                 const unsigned bits = __builtin_bit_cast(unsigned, fmaxf(v, 0.f));
;                 key[k] = valid ? ((forced ? 0xFFFFFF00u : (bits & 0xFFFFFF00u)) | (unsigned)(255 - s)) : 0u; }
;             unsigned w0 = 0u, w1 = 0u, w2 = 0u, w3 = 0u;
	v_add_f32_e32 v2, v2, v4
	v_cndmask_b32_e64 v13, 0, v14, s[0:1]
	v_or_b32_e32 v14, 64, v21
	v_cmp_eq_u32_e64 s[0:1], s82, v14
	v_cmp_eq_u32_e64 s[6:7], s5, v14
	v_max_f32_e32 v2, 0, v2
	v_and_b32_e32 v2, 0xffffff00, v2
	s_or_b64 s[0:1], s[0:1], s[6:7]
	v_cndmask_b32_e64 v2, v2, v219, s[0:1]
	v_bitop3_b32 v2, v2, s71, v21 bitop3:0x36
	v_cmp_ge_i32_e64 s[0:1], s82, v14
	v_cmp_eq_u32_e64 s[6:7], s5, v15
	s_nop 0
	v_cndmask_b32_e64 v14, 0, v2, s[0:1]
	v_add_f32_e32 v2, v3, v5
	v_cmp_eq_u32_e64 s[0:1], s82, v15
	v_max_f32_e32 v2, 0, v2
	v_and_b32_e32 v2, 0xffffff00, v2
	s_or_b64 s[0:1], s[0:1], s[6:7]
	v_cndmask_b32_e64 v16, v2, v219, s[0:1]
	ds_read2_b32 v[2:3], v19 offset0:80 offset1:88
	ds_read2_b32 v[4:5], v20 offset0:80 offset1:88
	v_bitop3_b32 v16, v16, s72, v21 bitop3:0x36
	v_cmp_ge_i32_e64 s[0:1], s82, v15
	s_waitcnt lgkmcnt(0)
	v_add_f32_e32 v2, v2, v4
	v_cndmask_b32_e64 v15, 0, v16, s[0:1]
	v_or_b32_e32 v16, 0x50, v21
	v_cmp_eq_u32_e64 s[0:1], s82, v16
	v_cmp_eq_u32_e64 s[6:7], s5, v16
	v_max_f32_e32 v2, 0, v2
	v_and_b32_e32 v2, 0xffffff00, v2
	s_or_b64 s[0:1], s[0:1], s[6:7]
	v_cndmask_b32_e64 v2, v2, v219, s[0:1]
	v_bitop3_b32 v2, v2, s73, v21 bitop3:0x36
	v_cmp_ge_i32_e64 s[0:1], s82, v16
	v_cmp_eq_u32_e64 s[6:7], s5, v17
	s_nop 0
	v_cndmask_b32_e64 v16, 0, v2, s[0:1]
	v_add_f32_e32 v2, v3, v5
	v_cmp_eq_u32_e64 s[0:1], s82, v17
	v_max_f32_e32 v2, 0, v2
	v_and_b32_e32 v2, 0xffffff00, v2
	s_or_b64 s[0:1], s[0:1], s[6:7]
	v_cndmask_b32_e64 v18, v2, v219, s[0:1]
	ds_read2_b32 v[2:3], v19 offset0:96 offset1:104
	ds_read2_b32 v[4:5], v20 offset0:96 offset1:104
	v_bitop3_b32 v18, v18, s74, v21 bitop3:0x36
	v_cmp_ge_i32_e64 s[0:1], s82, v17
	s_waitcnt lgkmcnt(0)
	v_add_f32_e32 v2, v2, v4
	v_cndmask_b32_e64 v17, 0, v18, s[0:1]
	v_or_b32_e32 v18, 0x60, v21
	v_cmp_eq_u32_e64 s[0:1], s82, v18
	v_cmp_eq_u32_e64 s[6:7], s5, v18
	v_max_f32_e32 v2, 0, v2
	v_and_b32_e32 v2, 0xffffff00, v2
	s_or_b64 s[0:1], s[0:1], s[6:7]
	v_cndmask_b32_e64 v2, v2, v219, s[0:1]
	v_bitop3_b32 v2, v2, s75, v21 bitop3:0x36
	v_cmp_ge_i32_e64 s[0:1], s82, v18
	v_cmp_eq_u32_e64 s[6:7], s5, v22
	s_nop 0
	v_cndmask_b32_e64 v18, 0, v2, s[0:1]
	v_add_f32_e32 v2, v3, v5
	v_cmp_eq_u32_e64 s[0:1], s82, v22
	v_max_f32_e32 v2, 0, v2
	v_and_b32_e32 v2, 0xffffff00, v2
	s_or_b64 s[0:1], s[0:1], s[6:7]
	v_cndmask_b32_e64 v23, v2, v219, s[0:1]
	ds_read2_b32 v[2:3], v19 offset0:112 offset1:120
	ds_read2_b32 v[4:5], v20 offset0:112 offset1:120
	v_bitop3_b32 v19, v23, s76, v21 bitop3:0x36
	v_cmp_ge_i32_e64 s[0:1], s82, v22
	v_or_b32_e32 v20, 0x70, v21
	v_cmp_eq_u32_e64 s[6:7], s5, v20
	s_waitcnt lgkmcnt(0)
	v_add_f32_e32 v2, v2, v4
	v_cndmask_b32_e64 v19, 0, v19, s[0:1]
	v_cmp_eq_u32_e64 s[0:1], s82, v20
	v_max_f32_e32 v2, 0, v2
	v_and_b32_e32 v2, 0xffffff00, v2
	s_or_b64 s[0:1], s[0:1], s[6:7]
	v_cndmask_b32_e64 v2, v2, v219, s[0:1]
	v_bitop3_b32 v2, v2, s77, v21 bitop3:0x36
	v_cmp_ge_i32_e64 s[0:1], s82, v20
	v_add_f32_e32 v3, v3, v5
	v_max_f32_e32 v3, 0, v3
	v_cndmask_b32_e64 v20, 0, v2, s[0:1]
	v_or_b32_e32 v2, 0x78, v21
	v_cmp_eq_u32_e64 s[0:1], s82, v2
	v_cmp_eq_u32_e64 s[6:7], s5, v2
	v_and_b32_e32 v3, 0xffffff00, v3
	s_or_b64 s[0:1], s[0:1], s[6:7]
	v_cndmask_b32_e64 v3, v3, v219, s[0:1]
	v_bitop3_b32 v3, v3, s78, v21 bitop3:0x36
	v_cmp_ge_i32_e64 s[0:1], s82, v2
	v_xor_b32_e32 v22, 4, v82
	v_xor_b32_e32 v23, 8, v82
	v_cndmask_b32_e64 v21, 0, v3, s[0:1]
	v_mov_b32_e32 v2, 0
	v_mov_b32_e32 v3, 0
	v_mov_b32_e32 v4, 0
	v_mov_b32_e32 v5, 0
	v_mov_b32_e32 v25, 0
	s_branch .LBB0_2749

; DEV unsigned shxu(unsigned v, int m, int lane) { return (unsigned)__builtin_amdgcn_ds_bpermute((lane ^ m) << 2, (int)v); }
; DEV void attn_nsa_phase(LAS unsigned char* lds, unsigned char* ws, int tid0, int G, int c) {
;     ...
;             for (int round = 0; round < 16; ++round) {
;                 unsigned m = 0u;
; #pragma unroll
;                 for (int k = 0; k < 16; ++k) m = key[k] > m ? key[k] : m;
;                 { unsigned t = shxu(m, 1, lane); m = t > m ? t : m; t = shxu(m, 2, lane); m = t > m ? t : m; t = shxu(m, 4, lane); m = t > m ? t : m; }
;                 if (m != 0u) { const int s = 255 - (int)(m & 255u); const unsigned bit = 1u << (s & 31); const int sw = s >> 5;
;                     w0 |= sw == 0 ? bit : 0u; w1 |= sw == 1 ? bit : 0u; w2 |= sw == 2 ? bit : 0u; w3 |= sw == 3 ? bit : 0u;
; #pragma unroll
;                     for (int k = 0; k < 16; ++k) key[k] = key[k] == m ? 0u : key[k]; }
;             }
.LBB0_2749:
	v_sub_u32_e32 v26, v6, v25
	v_sub_u32_e32 v27, v7, v25
	v_max_u32_e32 v26, v26, v27
	v_sub_u32_e32 v27, v8, v25
	v_sub_u32_e32 v28, v9, v25
	v_max3_u32 v26, v27, v28, v26
	v_sub_u32_e32 v27, v10, v25
	v_sub_u32_e32 v28, v11, v25
	v_max3_u32 v26, v27, v28, v26
	v_sub_u32_e32 v27, v12, v25
	v_sub_u32_e32 v28, v13, v25
	v_max3_u32 v26, v27, v28, v26
	v_sub_u32_e32 v27, v14, v25
	v_sub_u32_e32 v28, v15, v25
	v_max3_u32 v26, v27, v28, v26
	v_sub_u32_e32 v27, v16, v25
	v_sub_u32_e32 v28, v17, v25
	v_max3_u32 v26, v27, v28, v26
	v_sub_u32_e32 v27, v18, v25
	v_sub_u32_e32 v28, v19, v25
	v_max3_u32 v26, v27, v28, v26
	v_sub_u32_e32 v27, v20, v25
	v_sub_u32_e32 v28, v21, v25
	v_max3_u32 v26, v27, v28, v26
	s_nop 1
	v_max_u32_dpp v26, v26, v26 quad_perm:[1,0,3,2] row_mask:0xf bank_mask:0xf bound_ctrl:1
	s_nop 1
	v_max_u32_dpp v26, v26, v26 quad_perm:[2,3,0,1] row_mask:0xf bank_mask:0xf bound_ctrl:1
	s_nop 1
	v_max_u32_dpp v26, v26, v26 row_half_mirror row_mask:0xf bank_mask:0xf bound_ctrl:1
	v_add_u32_e32 v25, v25, v26
	v_cmp_ne_u32_e64 s[0:1], 0, v25
	s_and_saveexec_b64 s[6:7], s[0:1]
	s_cbranch_execz .LBB0_2748
	v_not_b32_e32 v26, v25
	v_bitop3_b32 v27, v25, s67, v25 bitop3:0xc
	v_lshlrev_b32_e64 v28, v26, 1
	v_bfe_u32 v26, v26, 5, 3
	v_cmp_gt_u32_e64 s[0:1], 32, v27
	s_nop 1
	v_cndmask_b32_e64 v27, 0, v28, s[0:1]
	v_cmp_eq_u32_e64 s[0:1], 1, v26
	v_or_b32_e32 v2, v27, v2
	s_nop 0
	v_cndmask_b32_e64 v29, 0, v28, s[0:1]
	v_cmp_eq_u32_e64 s[0:1], 2, v26
	v_or_b32_e32 v3, v29, v3
	s_nop 0
	v_cndmask_b32_e64 v30, 0, v28, s[0:1]
	v_cmp_eq_u32_e64 s[0:1], 3, v26
	v_or_b32_e32 v4, v30, v4
	s_nop 0
	v_cndmask_b32_e64 v26, 0, v28, s[0:1]
	v_or_b32_e32 v5, v26, v5
	s_branch .LBB0_2748
